# stack13: stack12 + gMLP unit: next unit's raw tile loads issued one unit ahead
# baseline (speedup 1.0000x reference)
; #define LDSP __attribute__((address_space(3)))
; DI unsigned pk2(float a, float b) { f32x2 v = {a, b}; bf2_t r = __builtin_convertvector(v, bf2_t); return __builtin_bit_cast(unsigned, r); }
; DI void gmlp_unit(const Params& p, int l, int T, int g, ldsp_t smem) {
;     ...
;     {
;         const int q = tid >> 2, part = tid & 3;
;         const bf16_t* src = p.U + (size_t)(T * 128 + q) * 1024 + 512 + g * 128 + part * 32;
;         u32x4 raw[4];
; #pragma unroll
;         for (int i = 0; i < 4; ++i) raw[i] = *(const u32x4*)(src + i * 8);
;         float a = 0.f, b = 0.f;
; #pragma unroll
;         for (int i = 0; i < 4; ++i)
; #pragma unroll
;             for (int j = 0; j < 4; ++j) {
;                 const float lo = __uint_as_float(raw[i][j] << 16), hi = __uint_as_float(raw[i][j] & 0xffff0000u);
;                 a += lo + hi; b += lo * lo + hi * hi;
;             }
;         a += __shfl_xor(a, 1); a += __shfl_xor(a, 2);
;         b += __shfl_xor(b, 1); b += __shfl_xor(b, 2);
;         const float mean = a * (1.f / 128.f);
;         const float rstd = rsqrtf(fmaxf(b * (1.f / 128.f) - mean * mean, 0.f) + EPS);
;         const float* gn = p.gmlp_norm_g + l * 512 + g * 128 + part * 32;
; #pragma unroll
;         for (int i = 0; i < 4; ++i)
; #pragma unroll
;             for (int j = 0; j < 4; ++j) {
;                 const int c0 = part * 32 + i * 8 + j * 2;
;                 const float lo = __uint_as_float(raw[i][j] << 16), hi = __uint_as_float(raw[i][j] & 0xffff0000u);
;                 const unsigned w = pk2((lo - mean) * rstd * gn[i * 8 + j * 2], (hi - mean) * rstd * gn[i * 8 + j * 2 + 1]);
;                 *(LDSP bf16_t*)(smem + c0 * 256 + (((q >> 3) ^ (c0 & 15)) << 4) + (q & 7) * 2) = (bf16_t)(w & 0xffffu);
;                 *(LDSP bf16_t*)(smem + (c0 + 1) * 256 + (((q >> 3) ^ ((c0 + 1) & 15)) << 4) + (q & 7) * 2) = (bf16_t)(w >> 16);
;             }
;     }
;     __syncthreads();
;     const int prow = wid * 16 + fr;
;     const bf16_t* wsp = p.ws_bf + ((size_t)(l * 4 + g) * 128 + prow) * 128 + fq * 8;
;     bf16x8 a[4];
; #pragma unroll
;     for (int ks = 0; ks < 4; ++ks) a[ks] = *(const bf16x8*)(wsp + ks * 32);
.LBB0_174:
	s_load_dword s100, s[88:89], 0x0
	v_mov_b32_e32 v46, v252
	s_lshl_b32 s4, s11, 5
	s_and_b32 s31, s4, 0xffffff80
	v_ashrrev_i32_e32 v47, 2, v46
	v_add_u32_e32 v0, s31, v47
	v_ashrrev_i32_e32 v1, 31, v0
	s_and_b32 s34, s11, 3
	v_lshlrev_b64 v[0:1], 11, v[0:1]
	v_lshlrev_b32_e32 v2, 5, v46
	v_lshl_add_u64 v[0:1], s[16:17], 0, v[0:1]
	s_lshl_b32 s98, s34, 8
	v_and_b32_e32 v36, 0x60, v2
	v_lshl_add_u64 v[0:1], v[0:1], 0, s[98:99]
	v_lshlrev_b32_e32 v192, 1, v36
	s_waitcnt lgkmcnt(0)
	v_lshl_add_u64 v[4:5], v[0:1], 0, v[192:193]
	v_readlane_b32 s101, v253, 0
	s_nop 3
	s_cmp_lg_u32 s11, s101
	s_cbranch_scc1 .Lgp_have
	global_load_dwordx4 v[232:235], v[4:5], off offset:1072
	global_load_dwordx4 v[236:239], v[4:5], off offset:1056
	global_load_dwordx4 v[240:243], v[4:5], off offset:1040
	global_load_dwordx4 v[244:247], v[4:5], off offset:1024
	global_load_dword v184, v[4:5], off offset:1024
	global_load_dword v184, v[4:5], off offset:1024
	global_load_dword v184, v[4:5], off offset:1024
	global_load_dword v184, v[4:5], off offset:1024
.Lgp_have:
	s_lshl_b32 s101, s100, 16
	v_mov_b32_e32 v250, s101
	v_mov_b32_e32 v251, 0
	v_lshl_add_u64 v[248:249], v[4:5], 0, v[250:251]
	s_add_i32 s101, s11, s100
	v_cmp_lt_i32_e32 vcc, v134, v203
	v_lshlrev_b32_e32 v64, 2, v36
	v_lshlrev_b32_e32 v57, 8, v36
	v_ashrrev_i32_e32 v36, 1, v46
	v_and_b32_e32 v58, -16, v36
	v_add_u32_e32 v36, v57, v58
	s_lshl_b32 s4, s34, 9
	s_add_u32 s4, s9, s4
	s_addc_u32 s5, s10, 0
	s_movk_i32 s35, 0x50
	s_brev_b32 s36, 60
	v_lshrrev_b32_e32 v44, 4, v46
	v_and_b32_e32 v45, 15, v46
	s_waitcnt vmcnt(4)
	v_mov_b64_e32 v[0:1], v[232:233]
	v_mov_b64_e32 v[2:3], v[234:235]
	v_mov_b64_e32 v[10:11], v[236:237]
	v_mov_b64_e32 v[12:13], v[238:239]
	v_mov_b64_e32 v[22:23], v[240:241]
	v_mov_b64_e32 v[24:25], v[242:243]
	v_mov_b64_e32 v[38:39], v[244:245]
	v_mov_b64_e32 v[40:41], v[246:247]
	s_cmp_ge_i32 s101, s6
	s_cbranch_scc1 .Lgp_nopf
	global_load_dwordx4 v[232:235], v[248:249], off offset:1072
	global_load_dwordx4 v[236:239], v[248:249], off offset:1056
	global_load_dwordx4 v[240:243], v[248:249], off offset:1040
	global_load_dwordx4 v[244:247], v[248:249], off offset:1024
.Lgp_nopf:
	v_lshlrev_b32_e32 v4, 16, v2
	v_and_b32_e32 v26, 0xffff0000, v2
	v_lshlrev_b32_e32 v5, 16, v3
	v_and_b32_e32 v27, 0xffff0000, v3
	v_mov_b32_e32 v28, v4
	v_mov_b32_e32 v29, v26
	v_mul_f32_e32 v2, v26, v26
	v_pk_fma_f32 v[30:31], v[28:29], v[28:29], v[2:3] op_sel_hi:[1,1,0]
	v_pk_add_f32 v[2:3], v[4:5], v[26:27]
	v_mov_b32_e32 v26, v5
	v_mul_f32_e32 v4, v27, v27
	v_pk_fma_f32 v[32:33], v[26:27], v[26:27], v[4:5] op_sel_hi:[1,1,0]
	v_cndmask_b32_e32 v4, v202, v134, vcc
	v_cmp_lt_i32_e32 vcc, v135, v203
	v_lshlrev_b32_e32 v62, 2, v4
	s_nop 0
	v_and_b32_e32 v5, 0xffff0000, v38
	v_cndmask_b32_e32 v4, v202, v135, vcc
	v_lshlrev_b32_e32 v63, 2, v4
	v_lshlrev_b32_e32 v4, 1, v47
	v_and_b32_e32 v56, 14, v4
	v_or_b32_e32 v65, v36, v56
	v_xad_u32 v36, v58, 16, v57
	v_lshlrev_b32_e32 v34, 16, v38
	v_and_b32_e32 v4, s0, v38
	v_mov_b32_e32 v35, v5
	v_or_b32_e32 v66, v36, v56
	v_lshlrev_b32_e32 v36, 16, v39
	v_and_b32_e32 v37, 0xffff0000, v39
	v_pk_add_f32 v[42:43], v[34:35], v[4:5] op_sel_hi:[0,1]
	v_pk_mul_f32 v[38:39], v[36:37], v[36:37]
	v_pk_mul_f32 v[48:49], v[34:35], v[34:35]
	v_mov_b32_e32 v42, v38
	v_mov_b32_e32 v192, v39
	v_pk_add_f32 v[38:39], v[42:43], v[192:193]
	v_mov_b32_e32 v42, v48
	v_mov_b32_e32 v43, v36
	v_mov_b32_e32 v48, v49
	v_mov_b32_e32 v49, v37
	v_mov_b32_e32 v31, v2
	v_mov_b32_e32 v33, v3
	global_load_dwordx4 v[2:5], v64, s[4:5] offset:48
	global_load_dwordx4 v[6:9], v64, s[4:5] offset:32
	global_load_dwordx4 v[14:17], v64, s[4:5] offset:16
	global_load_dwordx4 v[18:21], v64, s[4:5]
	global_load_dwordx4 v[84:87], v64, s[4:5] offset:112
	global_load_dwordx4 v[88:91], v64, s[4:5] offset:96
	global_load_dwordx4 v[92:95], v64, s[4:5] offset:80
	global_load_dwordx4 v[96:99], v64, s[4:5] offset:64
	s_or_b32 s100, s34, s7
	s_lshl_b32 s100, s100, 7
	v_lshrrev_b32_e32 v116, 2, v252
	v_bfi_b32 v116, -16, v116, v252
	v_add_u32_e32 v117, s100, v116
	v_bfe_u32 v118, v252, 4, 2
	v_lshlrev_b32_e32 v119, 8, v117
	v_lshl_add_u32 v119, v118, 4, v119
	global_load_dwordx4 v[140:143], v119, s[64:65]
	global_load_dwordx4 v[144:147], v119, s[64:65] offset:64
	global_load_dwordx4 v[148:151], v119, s[64:65] offset:128
	global_load_dwordx4 v[152:155], v119, s[64:65] offset:192
	v_lshlrev_b32_e32 v117, 2, v117
	v_readlane_b32 s100, v253, 11
	v_readlane_b32 s101, v253, 12
	s_nop 4
	global_load_dword v156, v117, s[100:101]
	v_lshrrev_b32_e32 v120, 6, v252
	v_lshl_add_u32 v123, v120, 4, v118
	v_add_u32_e32 v123, s31, v123
	v_lshlrev_b32_e32 v123, 11, v123
	v_and_b32_e32 v128, 15, v252
	v_lshl_add_u32 v123, v128, 4, v123
	v_add_u32_e32 v124, s98, v123
	v_add_u32_e32 v125, 0x2000, v124
	v_add_u32_e32 v126, 0x4000, v124
	v_add_u32_e32 v127, 0x6000, v124
	global_load_dwordx4 v[168:171], v124, s[16:17]
	global_load_dwordx4 v[172:175], v125, s[16:17]
	global_load_dwordx4 v[176:179], v126, s[16:17]
	global_load_dwordx4 v[180:183], v127, s[16:17]
	v_mul_u32_u24_e32 v129, 0x1200, v120
	v_mul_u32_u24_e32 v130, 0x110, v118
	v_add_u32_e32 v121, v129, v130
	v_add_u32_e32 v121, 0x8000, v121
	v_lshl_add_u32 v121, v128, 4, v121
	v_mul_u32_u24_e32 v130, 0x110, v128
	v_add_u32_e32 v122, v129, v130
	v_add_u32_e32 v122, 0x8000, v122
	v_lshl_add_u32 v122, v118, 3, v122
	v_pk_add_f32 v[42:43], v[42:43], v[48:49]
	s_nop 0
	v_pk_add_f32 v[42:43], v[42:43], v[38:39]
	v_xad_u32 v38, v58, 32, v57
	v_or_b32_e32 v67, v38, v56
	v_xad_u32 v38, v58, 48, v57
	v_or_b32_e32 v68, v38, v56
	v_lshlrev_b32_e32 v38, 16, v40
	v_and_b32_e32 v39, 0xffff0000, v40
; DI void gmlp_unit(const Params& p, int l, int T, int g, ldsp_t smem) {
;     ...
;         float a = 0.f, b = 0.f;
; #pragma unroll
;         for (int i = 0; i < 4; ++i)
; #pragma unroll
;             for (int j = 0; j < 4; ++j) {
;                 const float lo = __uint_as_float(raw[i][j] << 16), hi = __uint_as_float(raw[i][j] & 0xffff0000u);
;                 a += lo + hi; b += lo * lo + hi * hi;
;             }
;         a += __shfl_xor(a, 1); a += __shfl_xor(a, 2);
;         b += __shfl_xor(b, 1); b += __shfl_xor(b, 2);
;         const float mean = a * (1.f / 128.f);
;         const float rstd = rsqrtf(fmaxf(b * (1.f / 128.f) - mean * mean, 0.f) + EPS);
	v_pk_mul_f32 v[48:49], v[38:39], v[38:39]
	v_xad_u32 v40, v58, 64, v57
	v_mov_b32_e32 v50, v48
	v_mov_b32_e32 v51, v38
	v_mov_b32_e32 v48, v49
	v_mov_b32_e32 v49, v39
	v_or_b32_e32 v69, v40, v56
	v_xad_u32 v40, v58, s35, v57
	v_pk_add_f32 v[48:49], v[50:51], v[48:49]
	v_or_b32_e32 v70, v40, v56
	v_lshlrev_b32_e32 v40, 16, v41
	v_and_b32_e32 v41, 0xffff0000, v41
	v_pk_add_f32 v[42:43], v[48:49], v[42:43]
	v_pk_mul_f32 v[48:49], v[40:41], v[40:41]
	v_mov_b32_e32 v51, v40
	v_mov_b32_e32 v50, v48
	v_mov_b32_e32 v48, v49
	v_mov_b32_e32 v49, v41
	v_pk_add_f32 v[48:49], v[50:51], v[48:49]
	s_movk_i32 s35, 0x60
	v_pk_add_f32 v[48:49], v[48:49], v[42:43]
	v_xad_u32 v42, v58, s35, v57
	v_or_b32_e32 v71, v42, v56
	v_xad_u32 v42, v58, s14, v57
	v_or_b32_e32 v72, v42, v56
	v_lshlrev_b32_e32 v42, 16, v22
	v_and_b32_e32 v43, 0xffff0000, v22
	v_pk_mul_f32 v[50:51], v[42:43], v[42:43]
	v_xad_u32 v22, v58, s8, v57
	s_movk_i32 s35, 0x90
	v_mov_b32_e32 v52, v50
	v_mov_b32_e32 v53, v42
	v_mov_b32_e32 v50, v51
	v_mov_b32_e32 v51, v43
	v_or_b32_e32 v73, v22, v56
	v_xad_u32 v22, v58, s35, v57
	v_pk_add_f32 v[50:51], v[52:53], v[50:51]
	v_or_b32_e32 v74, v22, v56
	v_lshlrev_b32_e32 v22, 16, v23
	v_and_b32_e32 v23, 0xffff0000, v23
	v_pk_add_f32 v[48:49], v[50:51], v[48:49]
	v_pk_mul_f32 v[50:51], v[22:23], v[22:23]
	v_mov_b32_e32 v53, v22
	v_mov_b32_e32 v52, v50
	v_mov_b32_e32 v50, v51
	v_mov_b32_e32 v51, v23
	v_pk_add_f32 v[50:51], v[52:53], v[50:51]
	s_movk_i32 s35, 0xa0
	v_pk_add_f32 v[48:49], v[50:51], v[48:49]
	v_xad_u32 v50, v58, s35, v57
	s_movk_i32 s35, 0xb0
	v_or_b32_e32 v75, v50, v56
	v_xad_u32 v50, v58, s35, v57
	v_or_b32_e32 v76, v50, v56
	v_lshlrev_b32_e32 v50, 16, v24
	v_and_b32_e32 v51, 0xffff0000, v24
	v_pk_mul_f32 v[52:53], v[50:51], v[50:51]
	v_xad_u32 v24, v58, s15, v57
	s_movk_i32 s35, 0xd0
	v_mov_b32_e32 v54, v52
	v_mov_b32_e32 v55, v50
	v_mov_b32_e32 v52, v53
	v_mov_b32_e32 v53, v51
	v_or_b32_e32 v77, v24, v56
	v_xad_u32 v24, v58, s35, v57
	v_pk_add_f32 v[52:53], v[54:55], v[52:53]
	v_or_b32_e32 v78, v24, v56
	v_lshlrev_b32_e32 v24, 16, v25
	v_and_b32_e32 v25, 0xffff0000, v25
	v_pk_add_f32 v[48:49], v[52:53], v[48:49]
	v_pk_mul_f32 v[52:53], v[24:25], v[24:25]
	v_mov_b32_e32 v55, v24
	v_mov_b32_e32 v54, v52
	v_mov_b32_e32 v52, v53
	v_mov_b32_e32 v53, v25
	v_pk_add_f32 v[52:53], v[54:55], v[52:53]
	s_movk_i32 s35, 0xe0
	v_pk_add_f32 v[48:49], v[52:53], v[48:49]
	v_xad_u32 v52, v58, s35, v57
	s_movk_i32 s35, 0xf0
	v_or_b32_e32 v79, v52, v56
	v_xad_u32 v52, v58, s35, v57
	v_or_b32_e32 v80, v52, v56
	v_lshlrev_b32_e32 v52, 16, v10
	v_and_b32_e32 v53, 0xffff0000, v10
	v_pk_mul_f32 v[54:55], v[52:53], v[52:53]
	v_mov_b32_e32 v57, v52
	v_mov_b32_e32 v56, v54
	v_mov_b32_e32 v54, v55
	v_mov_b32_e32 v55, v53
	v_pk_add_f32 v[54:55], v[56:57], v[54:55]
	s_nop 0
	v_pk_add_f32 v[48:49], v[54:55], v[48:49]
	v_lshlrev_b32_e32 v54, 16, v11
	v_and_b32_e32 v55, 0xffff0000, v11
	v_pk_mul_f32 v[10:11], v[54:55], v[54:55]
	v_mov_b32_e32 v57, v54
	v_mov_b32_e32 v56, v10
	v_mov_b32_e32 v10, v11
	v_mov_b32_e32 v11, v55
	v_pk_add_f32 v[10:11], v[56:57], v[10:11]
	s_nop 0
	v_pk_add_f32 v[10:11], v[10:11], v[48:49]
	v_lshlrev_b32_e32 v48, 16, v12
	v_and_b32_e32 v49, 0xffff0000, v12
	v_pk_mul_f32 v[56:57], v[48:49], v[48:49]
	v_mov_b32_e32 v59, v48
	v_mov_b32_e32 v58, v56
	v_mov_b32_e32 v56, v57
	v_mov_b32_e32 v57, v49
	v_pk_add_f32 v[56:57], v[58:59], v[56:57]
	s_nop 0
	v_pk_add_f32 v[10:11], v[56:57], v[10:11]
	v_lshlrev_b32_e32 v56, 16, v13
	v_and_b32_e32 v57, 0xffff0000, v13
	v_pk_mul_f32 v[12:13], v[56:57], v[56:57]
	v_mov_b32_e32 v59, v56
	v_mov_b32_e32 v58, v12
	v_mov_b32_e32 v12, v13
	v_mov_b32_e32 v13, v57
	v_pk_add_f32 v[12:13], v[58:59], v[12:13]
	v_lshlrev_b32_e32 v58, 16, v0
	v_and_b32_e32 v59, 0xffff0000, v0
	v_pk_add_f32 v[10:11], v[12:13], v[10:11]
	v_pk_mul_f32 v[12:13], v[58:59], v[58:59]
	v_mov_b32_e32 v61, v58
	v_mov_b32_e32 v60, v12
	v_mov_b32_e32 v12, v13
	v_mov_b32_e32 v13, v59
	v_pk_add_f32 v[12:13], v[60:61], v[12:13]
	v_lshlrev_b32_e32 v60, 16, v1
	v_and_b32_e32 v61, 0xffff0000, v1
	v_pk_mul_f32 v[0:1], v[60:61], v[60:61]
	v_pk_add_f32 v[10:11], v[12:13], v[10:11]
	v_mov_b32_e32 v12, v0
	v_mov_b32_e32 v13, v60
	v_mov_b32_e32 v0, v1
	v_mov_b32_e32 v1, v61
	v_pk_add_f32 v[0:1], v[12:13], v[0:1]
	s_nop 0
	v_pk_add_f32 v[0:1], v[0:1], v[10:11]
	s_nop 0
	v_pk_add_f32 v[0:1], v[30:31], v[0:1]
	s_nop 0
	v_pk_add_f32 v[0:1], v[32:33], v[0:1]
	ds_bpermute_b32 v11, v62, v1
	ds_bpermute_b32 v10, v62, v0
	s_waitcnt lgkmcnt(0)
	v_pk_add_f32 v[0:1], v[0:1], v[10:11]
	ds_bpermute_b32 v11, v63, v1
	ds_bpermute_b32 v10, v63, v0
	s_waitcnt lgkmcnt(0)
	v_pk_add_f32 v[0:1], v[0:1], v[10:11]
	s_nop 0
	v_pk_mul_f32 v[30:31], v[0:1], s[36:37] op_sel_hi:[1,0]
	v_readlane_b32 s36, v253, 3
	v_fma_f32 v0, -v31, v31, v30
	v_max_f32_e32 v0, 0, v0
	v_add_f32_e32 v0, 0x358637bd, v0
	v_cmp_gt_f32_e32 vcc, s92, v0
	v_mul_f32_e32 v1, 0x4b800000, v0
	v_readlane_b32 s44, v253, 11
	v_cndmask_b32_e32 v0, v0, v1, vcc
	v_rsq_f32_e32 v0, v0
	v_readlane_b32 s45, v253, 12
	v_readlane_b32 s37, v253, 4
	v_readlane_b32 s38, v253, 5
	v_mul_f32_e32 v1, 0x45800000, v0
	v_cndmask_b32_e32 v32, v0, v1, vcc
	v_pk_add_f32 v[0:1], v[34:35], v[30:31] op_sel:[0,1] neg_lo:[0,1] neg_hi:[0,1]
	v_bfi_b32 v34, -16, v47, v46
	v_pk_mul_f32 v[0:1], v[0:1], v[32:33] op_sel_hi:[1,0]
	v_ashrrev_i32_e32 v35, 31, v34
	s_waitcnt vmcnt(13)
; #define LDSP __attribute__((address_space(3)))
; DI unsigned pk2(float a, float b) { f32x2 v = {a, b}; bf2_t r = __builtin_convertvector(v, bf2_t); return __builtin_bit_cast(unsigned, r); }
; DI void gmlp_unit(const Params& p, int l, int T, int g, ldsp_t smem) {
;     ...
;         const float mean = a * (1.f / 128.f);
;         const float rstd = rsqrtf(fmaxf(b * (1.f / 128.f) - mean * mean, 0.f) + EPS);
;         const float* gn = p.gmlp_norm_g + l * 512 + g * 128 + part * 32;
; #pragma unroll
;         for (int i = 0; i < 4; ++i)
; #pragma unroll
;             for (int j = 0; j < 4; ++j) {
;                 const int c0 = part * 32 + i * 8 + j * 2;
;                 const float lo = __uint_as_float(raw[i][j] << 16), hi = __uint_as_float(raw[i][j] & 0xffff0000u);
;                 const unsigned w = pk2((lo - mean) * rstd * gn[i * 8 + j * 2], (hi - mean) * rstd * gn[i * 8 + j * 2 + 1]);
;                 *(LDSP bf16_t*)(smem + c0 * 256 + (((q >> 3) ^ (c0 & 15)) << 4) + (q & 7) * 2) = (bf16_t)(w & 0xffffu);
;                 *(LDSP bf16_t*)(smem + (c0 + 1) * 256 + (((q >> 3) ^ ((c0 + 1) & 15)) << 4) + (q & 7) * 2) = (bf16_t)(w >> 16);
;             }
;     }
;     __syncthreads();
	v_pk_mul_f32 v[0:1], v[18:19], v[0:1]
	v_readlane_b32 s39, v253, 6
	v_cvt_pk_bf16_f32 v0, v0, v1
	ds_write_b16 v65, v0
	ds_write_b16_d16_hi v66, v0 offset:256
	v_pk_add_f32 v[0:1], v[36:37], v[30:31] op_sel:[0,1] neg_lo:[0,1] neg_hi:[0,1]
	v_readlane_b32 s40, v253, 7
	v_pk_mul_f32 v[0:1], v[0:1], v[32:33] op_sel_hi:[1,0]
	v_readlane_b32 s41, v253, 8
	v_pk_mul_f32 v[0:1], v[20:21], v[0:1]
	v_readlane_b32 s42, v253, 9
	v_cvt_pk_bf16_f32 v0, v0, v1
	ds_write_b16 v67, v0 offset:512
	ds_write_b16_d16_hi v68, v0 offset:768
	v_pk_add_f32 v[0:1], v[38:39], v[30:31] op_sel:[0,1] neg_lo:[0,1] neg_hi:[0,1]
	v_readlane_b32 s43, v253, 10
	v_pk_mul_f32 v[0:1], v[0:1], v[32:33] op_sel_hi:[1,0]
	v_readlane_b32 s46, v253, 13
	v_pk_mul_f32 v[0:1], v[14:15], v[0:1]
	v_readlane_b32 s47, v253, 14
	v_cvt_pk_bf16_f32 v0, v0, v1
	ds_write_b16 v69, v0 offset:1024
	ds_write_b16_d16_hi v70, v0 offset:1280
	v_pk_add_f32 v[0:1], v[40:41], v[30:31] op_sel:[0,1] neg_lo:[0,1] neg_hi:[0,1]
	v_readlane_b32 s48, v253, 15
	v_pk_mul_f32 v[0:1], v[0:1], v[32:33] op_sel_hi:[1,0]
	v_readlane_b32 s49, v253, 16
	v_pk_mul_f32 v[0:1], v[16:17], v[0:1]
	v_readlane_b32 s50, v253, 17
	v_cvt_pk_bf16_f32 v0, v0, v1
	ds_write_b16 v71, v0 offset:1536
	ds_write_b16_d16_hi v72, v0 offset:1792
	v_pk_add_f32 v[0:1], v[42:43], v[30:31] op_sel:[0,1] neg_lo:[0,1] neg_hi:[0,1]
	v_readlane_b32 s51, v253, 18
	v_pk_mul_f32 v[0:1], v[0:1], v[32:33] op_sel_hi:[1,0]
	s_nop 0
	v_pk_mul_f32 v[0:1], v[6:7], v[0:1]
	s_nop 0
	v_cvt_pk_bf16_f32 v0, v0, v1
	ds_write_b16 v73, v0 offset:2048
	ds_write_b16_d16_hi v74, v0 offset:2304
	v_pk_add_f32 v[0:1], v[22:23], v[30:31] op_sel:[0,1] neg_lo:[0,1] neg_hi:[0,1]
	s_nop 0
	v_pk_mul_f32 v[0:1], v[0:1], v[32:33] op_sel_hi:[1,0]
	s_nop 0
	v_pk_mul_f32 v[0:1], v[8:9], v[0:1]
	s_nop 0
	v_cvt_pk_bf16_f32 v0, v0, v1
	ds_write_b16 v75, v0 offset:2560
	ds_write_b16_d16_hi v76, v0 offset:2816
	v_pk_add_f32 v[0:1], v[50:51], v[30:31] op_sel:[0,1] neg_lo:[0,1] neg_hi:[0,1]
	s_nop 0
	v_pk_mul_f32 v[0:1], v[0:1], v[32:33] op_sel_hi:[1,0]
	s_nop 0
	v_pk_mul_f32 v[0:1], v[0:1], v[2:3]
	s_nop 0
	v_cvt_pk_bf16_f32 v0, v0, v1
	ds_write_b16 v77, v0 offset:3072
	ds_write_b16_d16_hi v78, v0 offset:3328
	v_pk_add_f32 v[0:1], v[24:25], v[30:31] op_sel:[0,1] neg_lo:[0,1] neg_hi:[0,1]
	s_nop 0
	v_pk_mul_f32 v[0:1], v[0:1], v[32:33] op_sel_hi:[1,0]
	s_nop 0
	v_pk_mul_f32 v[0:1], v[0:1], v[4:5]
	s_nop 0
	v_cvt_pk_bf16_f32 v0, v0, v1
	ds_write_b16 v79, v0 offset:3584
	ds_write_b16_d16_hi v80, v0 offset:3840
	v_pk_add_f32 v[0:1], v[52:53], v[30:31] op_sel:[0,1] neg_lo:[0,1] neg_hi:[0,1]
	s_nop 0
	v_pk_mul_f32 v[16:17], v[0:1], v[32:33] op_sel_hi:[1,0]
	s_nop 0
	s_nop 0
	s_nop 0
	s_nop 0
	s_or_b32 s4, s34, s7
	s_ashr_i32 s5, s4, 31
	s_lshl_b64 s[4:5], s[4:5], 7
	s_waitcnt vmcnt(9)
	v_pk_mul_f32 v[12:13], v[16:17], v[96:97]
	s_nop 0
	v_cvt_pk_bf16_f32 v12, v12, v13
	ds_write_b16 v65, v12 offset:4096
	ds_write_b16_d16_hi v66, v12 offset:4352
	v_pk_add_f32 v[12:13], v[54:55], v[30:31] op_sel:[0,1] neg_lo:[0,1] neg_hi:[0,1]
	s_nop 0
	v_pk_mul_f32 v[12:13], v[12:13], v[32:33] op_sel_hi:[1,0]
	s_nop 0
	v_pk_mul_f32 v[12:13], v[12:13], v[98:99]
	s_nop 0
	v_cvt_pk_bf16_f32 v12, v12, v13
	ds_write_b16 v67, v12 offset:4608
	ds_write_b16_d16_hi v68, v12 offset:4864
	v_pk_add_f32 v[12:13], v[48:49], v[30:31] op_sel:[0,1] neg_lo:[0,1] neg_hi:[0,1]
	s_nop 0
	v_pk_mul_f32 v[12:13], v[12:13], v[32:33] op_sel_hi:[1,0]
	s_nop 0
	v_pk_mul_f32 v[8:9], v[12:13], v[92:93]
	s_nop 0
	v_cvt_pk_bf16_f32 v8, v8, v9
	ds_write_b16 v69, v8 offset:5120
	ds_write_b16_d16_hi v70, v8 offset:5376
	v_pk_add_f32 v[8:9], v[56:57], v[30:31] op_sel:[0,1] neg_lo:[0,1] neg_hi:[0,1]
	s_nop 0
	v_pk_mul_f32 v[8:9], v[8:9], v[32:33] op_sel_hi:[1,0]
	s_nop 0
	v_pk_mul_f32 v[8:9], v[8:9], v[94:95]
	s_nop 0
	v_cvt_pk_bf16_f32 v8, v8, v9
	ds_write_b16 v71, v8 offset:5632
	ds_write_b16_d16_hi v72, v8 offset:5888
	v_pk_add_f32 v[8:9], v[58:59], v[30:31] op_sel:[0,1] neg_lo:[0,1] neg_hi:[0,1]
	s_nop 0
	v_pk_mul_f32 v[8:9], v[8:9], v[32:33] op_sel_hi:[1,0]
	s_nop 0
	v_pk_mul_f32 v[4:5], v[8:9], v[88:89]
	s_nop 0
	v_cvt_pk_bf16_f32 v4, v4, v5
	ds_write_b16 v73, v4 offset:6144
	ds_write_b16_d16_hi v74, v4 offset:6400
	v_pk_add_f32 v[4:5], v[60:61], v[30:31] op_sel:[0,1] neg_lo:[0,1] neg_hi:[0,1]
	s_nop 0
	v_pk_mul_f32 v[4:5], v[4:5], v[32:33] op_sel_hi:[1,0]
	s_nop 0
	v_pk_mul_f32 v[4:5], v[4:5], v[90:91]
	s_nop 0
	v_cvt_pk_bf16_f32 v4, v4, v5
	ds_write_b16 v75, v4 offset:6656
	ds_write_b16_d16_hi v76, v4 offset:6912
	v_pk_add_f32 v[4:5], v[28:29], v[30:31] op_sel:[0,1] neg_lo:[0,1] neg_hi:[0,1]
	s_nop 0
	v_pk_mul_f32 v[4:5], v[4:5], v[32:33] op_sel_hi:[1,0]
	s_nop 0
	v_pk_mul_f32 v[0:1], v[4:5], v[84:85]
	v_bfe_u32 v4, v46, 4, 2
	v_cvt_pk_bf16_f32 v0, v0, v1
	ds_write_b16 v77, v0 offset:7168
	ds_write_b16_d16_hi v78, v0 offset:7424
	v_pk_add_f32 v[0:1], v[26:27], v[30:31] op_sel:[0,1] neg_lo:[0,1] neg_hi:[0,1]
	v_lshlrev_b32_e32 v5, 8, v45
	v_pk_mul_f32 v[0:1], v[0:1], v[32:33] op_sel_hi:[1,0]
	v_lshl_add_u64 v[32:33], s[4:5], 0, v[34:35]
	v_pk_mul_f32 v[0:1], v[0:1], v[86:87]
	v_lshlrev_b32_e32 v2, 4, v4
	v_cvt_pk_bf16_f32 v0, v0, v1
	ds_write_b16 v79, v0 offset:7680
	ds_write_b16_d16_hi v80, v0 offset:7936
	v_lshlrev_b64 v[0:1], 8, v[32:33]
	v_lshl_add_u64 v[0:1], s[64:65], 0, v[0:1]
	v_mov_b32_e32 v3, v193
	v_lshl_add_u64 v[6:7], v[0:1], 0, v[2:3]
	s_waitcnt lgkmcnt(0)
	s_barrier
; #define LDSP __attribute__((address_space(3)))
; DI void gmlp_unit(const Params& p, int l, int T, int g, ldsp_t smem) {
;     ...
;     const int prow = wid * 16 + fr;
;     const bf16_t* wsp = p.ws_bf + ((size_t)(l * 4 + g) * 128 + prow) * 128 + fq * 8;
;     bf16x8 a[4];
; #pragma unroll
;     for (int ks = 0; ks < 4; ++ks) a[ks] = *(const bf16x8*)(wsp + ks * 32);
;     f32x4 acc[8];
; #pragma unroll
;     for (int n = 0; n < 8; ++n) {
;         acc[n] = (f32x4){0.f, 0.f, 0.f, 0.f};
;         const int c = n * 16 + fr;
; #pragma unroll
;         for (int ks = 0; ks < 4; ++ks) {
;             const bf16x8 bq = *(const LDSP bf16x8*)(smem + c * 256 + (((ks * 4 + fq) ^ (c & 15)) << 4));
;             acc[n] = __builtin_amdgcn_mfma_f32_16x16x32_bf16(bq, a[ks], acc[n], 0, 0, 0);
;         }
;     }
;     const float bs = p.b_spatial[(size_t)(l * 4 + g) * 128 + prow];
	s_nop 0
	s_nop 0
	s_nop 0
	s_nop 0
	v_bitop3_b32 v6, v44, v45, 3 bitop3:0x6c
	v_lshl_or_b32 v35, v6, 4, v5
	ds_read_b128 v[6:9], v35
	v_bitop3_b32 v10, v4, v45, 4 bitop3:0x36
	v_lshl_or_b32 v44, v10, 4, v5
	ds_read_b128 v[10:13], v44
	s_waitcnt vmcnt(8) lgkmcnt(1)
	v_mfma_f32_16x16x32_bf16 v[6:9], v[6:9], v[140:143], 0
	v_lshlrev_b32_e32 v192, 3, v4
	ds_read_b128 v[50:53], v44 offset:24576
	v_add_u32_e32 v34, s31, v34
	s_waitcnt vmcnt(7) lgkmcnt(1)
	v_mfma_f32_16x16x32_bf16 v[6:9], v[10:13], v[144:147], v[6:9]
	v_bitop3_b32 v10, v4, v45, 8 bitop3:0x36
	v_lshl_or_b32 v54, v10, 4, v5
	ds_read_b128 v[10:13], v54
	v_bitop3_b32 v4, v4, v45, 12 bitop3:0x36
	v_lshl_or_b32 v45, v4, 4, v5
	s_waitcnt vmcnt(5) lgkmcnt(0)
	v_mfma_f32_16x16x32_bf16 v[6:9], v[10:13], v[148:151], v[6:9]
	ds_read_b128 v[10:13], v45
	v_lshl_add_u64 v[32:33], v[32:33], 2, s[44:45]
	s_nop 0
	s_waitcnt vmcnt(5) lgkmcnt(0)
	v_mfma_f32_16x16x32_bf16 v[28:31], v[10:13], v[152:155], v[6:9]
	s_nop 2
	ds_read_b128 v[4:7], v35 offset:4096
	ds_read_b128 v[8:11], v44 offset:4096
	s_waitcnt vmcnt(4)
	v_mov_b32_e32 v32, v156
	s_nop 1
	v_pk_add_f32 v[28:29], v[28:29], v[32:33] op_sel_hi:[1,0]
	s_waitcnt lgkmcnt(1)
	v_mfma_f32_16x16x32_bf16 v[4:7], v[4:7], v[140:143], 0
	v_add_f32_e64 v30, v30, v32
	v_add_f32_e64 v31, v31, v32
	s_waitcnt lgkmcnt(0)
	v_mfma_f32_16x16x32_bf16 v[4:7], v[8:11], v[144:147], v[4:7]
	ds_read_b128 v[8:11], v54 offset:4096
	s_waitcnt lgkmcnt(0)
	v_mfma_f32_16x16x32_bf16 v[4:7], v[8:11], v[148:151], v[4:7]
	ds_read_b128 v[8:11], v45 offset:4096
	s_waitcnt lgkmcnt(0)
	v_mfma_f32_16x16x32_bf16 v[24:27], v[8:11], v[152:155], v[4:7]
	s_nop 4
	ds_read_b128 v[4:7], v35 offset:8192
	ds_read_b128 v[8:11], v44 offset:8192
	s_nop 0
	v_pk_add_f32 v[24:25], v[24:25], v[32:33] op_sel_hi:[1,0]
	s_waitcnt lgkmcnt(1)
	v_mfma_f32_16x16x32_bf16 v[4:7], v[4:7], v[140:143], 0
	v_add_f32_e64 v26, v26, v32
	v_add_f32_e64 v27, v27, v32
	s_waitcnt lgkmcnt(0)
	v_mfma_f32_16x16x32_bf16 v[4:7], v[8:11], v[144:147], v[4:7]
	ds_read_b128 v[8:11], v54 offset:8192
	s_waitcnt lgkmcnt(0)
	v_mfma_f32_16x16x32_bf16 v[4:7], v[8:11], v[148:151], v[4:7]
	ds_read_b128 v[8:11], v45 offset:8192
	s_waitcnt lgkmcnt(0)
	v_mfma_f32_16x16x32_bf16 v[20:23], v[8:11], v[152:155], v[4:7]
	s_nop 4
	ds_read_b128 v[4:7], v35 offset:12288
	ds_read_b128 v[8:11], v44 offset:12288
	s_nop 0
	v_pk_add_f32 v[20:21], v[20:21], v[32:33] op_sel_hi:[1,0]
	s_waitcnt lgkmcnt(1)
	v_mfma_f32_16x16x32_bf16 v[4:7], v[4:7], v[140:143], 0
	v_add_f32_e64 v22, v22, v32
	v_add_f32_e64 v23, v23, v32
	s_waitcnt lgkmcnt(0)
	v_mfma_f32_16x16x32_bf16 v[4:7], v[8:11], v[144:147], v[4:7]
	ds_read_b128 v[8:11], v54 offset:12288
	s_waitcnt lgkmcnt(0)
	v_mfma_f32_16x16x32_bf16 v[4:7], v[8:11], v[148:151], v[4:7]
	ds_read_b128 v[8:11], v45 offset:12288
	s_waitcnt lgkmcnt(0)
	v_mfma_f32_16x16x32_bf16 v[16:19], v[8:11], v[152:155], v[4:7]
	s_nop 4
	ds_read_b128 v[4:7], v35 offset:16384
	ds_read_b128 v[8:11], v44 offset:16384
	s_nop 0
	v_pk_add_f32 v[16:17], v[16:17], v[32:33] op_sel_hi:[1,0]
	s_waitcnt lgkmcnt(1)
	v_mfma_f32_16x16x32_bf16 v[4:7], v[4:7], v[140:143], 0
	v_add_f32_e64 v18, v18, v32
	v_add_f32_e64 v19, v19, v32
	s_waitcnt lgkmcnt(0)
	v_mfma_f32_16x16x32_bf16 v[4:7], v[8:11], v[144:147], v[4:7]
	ds_read_b128 v[8:11], v54 offset:16384
	s_waitcnt lgkmcnt(0)
	v_mfma_f32_16x16x32_bf16 v[4:7], v[8:11], v[148:151], v[4:7]
	ds_read_b128 v[8:11], v45 offset:16384
	s_waitcnt lgkmcnt(0)
	v_mfma_f32_16x16x32_bf16 v[12:15], v[8:11], v[152:155], v[4:7]
	s_nop 4
	ds_read_b128 v[4:7], v35 offset:20480
	ds_read_b128 v[8:11], v44 offset:20480
	s_nop 0
	v_pk_add_f32 v[12:13], v[12:13], v[32:33] op_sel_hi:[1,0]
	s_waitcnt lgkmcnt(1)
	v_mfma_f32_16x16x32_bf16 v[4:7], v[4:7], v[140:143], 0
	v_add_f32_e64 v14, v14, v32
	v_add_f32_e64 v15, v15, v32
	s_waitcnt lgkmcnt(0)
	v_mfma_f32_16x16x32_bf16 v[4:7], v[8:11], v[144:147], v[4:7]
	ds_read_b128 v[8:11], v54 offset:20480
	s_waitcnt lgkmcnt(0)
	v_mfma_f32_16x16x32_bf16 v[4:7], v[8:11], v[148:151], v[4:7]
	ds_read_b128 v[8:11], v45 offset:20480
	s_waitcnt lgkmcnt(0)
	v_mfma_f32_16x16x32_bf16 v[8:11], v[8:11], v[152:155], v[4:7]
	s_nop 4
	ds_read_b128 v[4:7], v35 offset:24576
	s_nop 1
	v_pk_add_f32 v[8:9], v[8:9], v[32:33] op_sel_hi:[1,0]
	s_waitcnt lgkmcnt(0)
	v_mfma_f32_16x16x32_bf16 v[4:7], v[4:7], v[140:143], 0
	v_add_f32_e64 v10, v10, v32
	v_add_f32_e64 v11, v11, v32
	v_mfma_f32_16x16x32_bf16 v[4:7], v[50:53], v[144:147], v[4:7]
	ds_read_b128 v[50:53], v54 offset:24576
	s_waitcnt lgkmcnt(0)
	v_mfma_f32_16x16x32_bf16 v[4:7], v[50:53], v[148:151], v[4:7]
	ds_read_b128 v[50:53], v45 offset:24576
	s_waitcnt lgkmcnt(0)
	v_mfma_f32_16x16x32_bf16 v[4:7], v[50:53], v[152:155], v[4:7]
	ds_read_b128 v[50:53], v35 offset:28672
	v_ashrrev_i32_e32 v35, 31, v34
	s_nop 5
	v_pk_add_f32 v[4:5], v[4:5], v[32:33] op_sel_hi:[1,0]
	s_waitcnt lgkmcnt(0)
; DI unsigned pk2(float a, float b) { f32x2 v = {a, b}; bf2_t r = __builtin_convertvector(v, bf2_t); return __builtin_bit_cast(unsigned, r); }
; DI void gmlp_unit(const Params& p, int l, int T, int g, ldsp_t smem) {
;     ...
;     const float bs = p.b_spatial[(size_t)(l * 4 + g) * 128 + prow];
;     const int row = T * 128 + prow;
;     const bf16_t* up = p.U + (size_t)row * 1024 + g * 128 + fq * 4;
;     bf16_t* mp = p.MIX + (size_t)row * DM + 512 + g * 128 + fq * 4;
; #pragma unroll
;     for (int n = 0; n < 8; ++n) {
;         const u32x2 uu = *(const u32x2*)(up + n * 16);
;         const float u0 = __uint_as_float(uu[0] << 16), u1 = __uint_as_float(uu[0] & 0xffff0000u), u2 = __uint_as_float(uu[1] << 16), u3 = __uint_as_float(uu[1] & 0xffff0000u);
;         u32x2 w; w[0] = pk2((acc[n][0] + bs) * u0, (acc[n][1] + bs) * u1); w[1] = pk2((acc[n][2] + bs) * u2, (acc[n][3] + bs) * u3);
;         *(u32x2*)(mp + n * 16) = w;
;     }
;     __syncthreads();
; DI void mixer_phase(const Params& p, int l, ldsp_t smem) {
;     ...
;     for (int u = blockIdx.x; u < nT * 4; u += gridDim.x) gmlp_unit(p, l, u >> 2, u & 3, smem);
	v_mfma_f32_16x16x32_bf16 v[0:3], v[50:53], v[140:143], 0
	ds_read_b128 v[50:53], v44 offset:28672
	v_pk_add_f32 v[6:7], v[6:7], v[32:33] op_sel_hi:[1,0]
	s_waitcnt lgkmcnt(0)
	v_mfma_f32_16x16x32_bf16 v[0:3], v[50:53], v[144:147], v[0:3]
	ds_read_b128 v[36:39], v54 offset:28672
	s_waitcnt lgkmcnt(0)
	v_mfma_f32_16x16x32_bf16 v[0:3], v[36:39], v[148:151], v[0:3]
	ds_read_b128 v[36:39], v45 offset:28672
	s_waitcnt lgkmcnt(0)
	v_mfma_f32_16x16x32_bf16 v[0:3], v[36:39], v[152:155], v[0:3]
	v_lshlrev_b64 v[36:37], 11, v[34:35]
	v_lshl_add_u64 v[34:35], s[16:17], 0, v[36:37]
	v_lshl_add_u64 v[34:35], v[34:35], 0, s[98:99]
	v_lshl_add_u64 v[34:35], v[34:35], 0, v[192:193]
	s_nop 0
	v_lshl_add_u64 v[36:37], s[18:19], 0, v[36:37]
	v_lshl_add_u64 v[36:37], v[36:37], 0, s[98:99]
	v_lshl_add_u64 v[36:37], v[36:37], 0, v[192:193]
	v_pk_add_f32 v[0:1], v[0:1], v[32:33] op_sel_hi:[1,0]
	v_pk_add_f32 v[2:3], v[2:3], v[32:33] op_sel_hi:[1,0]
	s_waitcnt vmcnt(0)
	ds_write_b128 v121, v[168:171]
	ds_write_b128 v121, v[172:175] offset:1088
	ds_write_b128 v121, v[176:179] offset:2176
	ds_write_b128 v121, v[180:183] offset:3264
	ds_read_b64 v[100:101], v122
	ds_read_b64 v[102:103], v122 offset:32
	ds_read_b64 v[104:105], v122 offset:64
	ds_read_b64 v[106:107], v122 offset:96
	ds_read_b64 v[108:109], v122 offset:128
	ds_read_b64 v[110:111], v122 offset:160
	ds_read_b64 v[112:113], v122 offset:192
	ds_read_b64 v[114:115], v122 offset:224
	s_waitcnt lgkmcnt(0)
	v_lshlrev_b32_e32 v160, 16, v100
	v_and_b32_e32 v161, 0xffff0000, v100
	v_lshlrev_b32_e32 v162, 16, v101
	v_and_b32_e32 v163, 0xffff0000, v101
	v_pk_mul_f32 v[28:29], v[28:29], v[160:161]
	v_pk_mul_f32 v[30:31], v[30:31], v[162:163]
	v_cvt_pk_bf16_f32 v28, v28, v29
	v_cvt_pk_bf16_f32 v29, v30, v31
	ds_write_b64 v122, v[28:29]
	v_lshlrev_b32_e32 v160, 16, v102
	v_and_b32_e32 v161, 0xffff0000, v102
	v_lshlrev_b32_e32 v162, 16, v103
	v_and_b32_e32 v163, 0xffff0000, v103
	v_pk_mul_f32 v[24:25], v[24:25], v[160:161]
	v_pk_mul_f32 v[26:27], v[26:27], v[162:163]
	v_cvt_pk_bf16_f32 v24, v24, v25
	v_cvt_pk_bf16_f32 v25, v26, v27
	ds_write_b64 v122, v[24:25] offset:32
	v_lshlrev_b32_e32 v160, 16, v104
	v_and_b32_e32 v161, 0xffff0000, v104
	v_lshlrev_b32_e32 v162, 16, v105
	v_and_b32_e32 v163, 0xffff0000, v105
	v_pk_mul_f32 v[20:21], v[20:21], v[160:161]
	v_pk_mul_f32 v[22:23], v[22:23], v[162:163]
	v_cvt_pk_bf16_f32 v20, v20, v21
	v_cvt_pk_bf16_f32 v21, v22, v23
	ds_write_b64 v122, v[20:21] offset:64
	v_lshlrev_b32_e32 v160, 16, v106
	v_and_b32_e32 v161, 0xffff0000, v106
	v_lshlrev_b32_e32 v162, 16, v107
	v_and_b32_e32 v163, 0xffff0000, v107
	v_pk_mul_f32 v[16:17], v[16:17], v[160:161]
	v_pk_mul_f32 v[18:19], v[18:19], v[162:163]
	v_cvt_pk_bf16_f32 v16, v16, v17
	v_cvt_pk_bf16_f32 v17, v18, v19
	ds_write_b64 v122, v[16:17] offset:96
	v_lshlrev_b32_e32 v160, 16, v108
	v_and_b32_e32 v161, 0xffff0000, v108
	v_lshlrev_b32_e32 v162, 16, v109
	v_and_b32_e32 v163, 0xffff0000, v109
	v_pk_mul_f32 v[12:13], v[12:13], v[160:161]
	v_pk_mul_f32 v[14:15], v[14:15], v[162:163]
	v_cvt_pk_bf16_f32 v12, v12, v13
	v_cvt_pk_bf16_f32 v13, v14, v15
	ds_write_b64 v122, v[12:13] offset:128
	v_lshlrev_b32_e32 v160, 16, v110
	v_and_b32_e32 v161, 0xffff0000, v110
	v_lshlrev_b32_e32 v162, 16, v111
	v_and_b32_e32 v163, 0xffff0000, v111
	v_pk_mul_f32 v[8:9], v[8:9], v[160:161]
	v_pk_mul_f32 v[10:11], v[10:11], v[162:163]
	v_cvt_pk_bf16_f32 v8, v8, v9
	v_cvt_pk_bf16_f32 v9, v10, v11
	ds_write_b64 v122, v[8:9] offset:160
	v_lshlrev_b32_e32 v160, 16, v112
	v_and_b32_e32 v161, 0xffff0000, v112
	v_lshlrev_b32_e32 v162, 16, v113
	v_and_b32_e32 v163, 0xffff0000, v113
	v_pk_mul_f32 v[4:5], v[4:5], v[160:161]
	v_pk_mul_f32 v[6:7], v[6:7], v[162:163]
	v_cvt_pk_bf16_f32 v4, v4, v5
	v_cvt_pk_bf16_f32 v5, v6, v7
	ds_write_b64 v122, v[4:5] offset:192
	v_lshlrev_b32_e32 v160, 16, v114
	v_and_b32_e32 v161, 0xffff0000, v114
	v_lshlrev_b32_e32 v162, 16, v115
	v_and_b32_e32 v163, 0xffff0000, v115
	v_pk_mul_f32 v[0:1], v[0:1], v[160:161]
	v_pk_mul_f32 v[2:3], v[2:3], v[162:163]
	v_cvt_pk_bf16_f32 v0, v0, v1
	v_cvt_pk_bf16_f32 v1, v2, v3
	ds_write_b64 v122, v[0:1] offset:224
	ds_read_b128 v[204:207], v121
	ds_read_b128 v[210:213], v121 offset:1088
	ds_read_b128 v[214:217], v121 offset:2176
	ds_read_b128 v[220:223], v121 offset:3264
	s_waitcnt lgkmcnt(0)
	global_store_dwordx4 v124, v[204:207], s[18:19] offset:1024 sc1
	global_store_dwordx4 v125, v[210:213], s[18:19] offset:1024 sc1
	global_store_dwordx4 v126, v[214:217], s[18:19] offset:1024 sc1
	global_store_dwordx4 v127, v[220:223], s[18:19] offset:1024 sc1
	s_barrier
	s_load_dword s4, s[88:89], 0x0
	s_waitcnt lgkmcnt(0)
	s_add_i32 s11, s4, s11
	s_cmp_ge_i32 s11, s6
	s_cbranch_scc0 .LBB0_174
